# stack + timed K/V-cache prefetch: wave 1 of a queue-first workgroup warms its sample item's cache slices in L2 once all but 3 workgroups of its XCD have arrived at the in-proj barrier
# baseline (speedup 1.0000x reference)
; __device__ __forceinline__ unsigned xb_ld(unsigned* p)              { return __hip_atomic_load(p, __ATOMIC_RELAXED, __HIP_MEMORY_SCOPE_AGENT); }
; __device__ __forceinline__ void attn_sample_item(const Args& a, int l, int n, LAS unsigned char* lds, int tid, int lane, int wave) {
;     ...
;     const float* ck = a.in[5] + (size_t)(l * NSB + n) * 128 * 128; const float* cv = a.in[6] + (size_t)(l * NSB + n) * 128 * 128;
;     float* oks = a.out + O_KS + (size_t)(l * NSB + n) * 128 * 128; float* ovs = a.out + O_VS + (size_t)(l * NSB + n) * 128 * 128;
;     const int c16 = tid & 15, kvh = c16 >> 3, sub = c16 & 7;
;     u32x4 qws[4], zws[4];
;     if (wave < 2) attn_prefetch<true>(proj, MP + n * LS, wave * 4, lane, qws, zws);
;     f32x4 kc[4][2], vc[4][2];
; #pragma unroll
;     for (int pass = 0; pass < 4; ++pass) {
;         const int r = pass * 32 + (tid >> 4);
;         kc[pass][0] = __builtin_nontemporal_load((const f32x4*)(ck + r * 128 + c16 * 8)); kc[pass][1] = __builtin_nontemporal_load((const f32x4*)(ck + r * 128 + c16 * 8 + 4));
; __device__ __forceinline__ void xcd_barrier(const XcdBarrier& b) {
;     asm volatile("s_waitcnt vmcnt(0)" ::: "memory");
;     __syncthreads();
;     if (threadIdx.x == 0) {
;         unsigned* bar = b.bar;
;         __builtin_amdgcn_s_waitcnt(0);
;         unsigned nloc = b.st[0], nx = b.st[1];
;         if (nloc == 0u) { xcd_barrier_complete(bar, b.x, nloc, nx); b.st[0] = nloc; b.st[1] = nx; }
;         const unsigned old = xb_add(&bar[XB_XSUB(b.x)], 1u);
;         const unsigned gen = old / nloc;
;         if (old + 1u == (gen + 1u) * nloc) {
;             __builtin_amdgcn_fence(__ATOMIC_RELEASE, "agent");
;             asm volatile("s_waitcnt vmcnt(0)" ::: "memory");
;             const unsigned og = xb_add(&bar[XB_TOP], 1u);
;             const unsigned tg = og / nx;
;             if (og + 1u == (tg + 1u) * nx) xb_add(&bar[XB_TOPGEN], 1u);
;             else XB_SPIN(xb_ld(&bar[XB_TOPGEN]) == tg, bar);
;             __builtin_amdgcn_fence(__ATOMIC_ACQUIRE, "agent");
;             xb_add(&bar[XB_XGEN(b.x)], 1u);
;             asm volatile("s_waitcnt vmcnt(0)" ::: "memory");
;         } else {
;             XB_SPIN(xb_ld(&bar[XB_XGEN(b.x)]) == gen, bar);
;             __builtin_amdgcn_fence(__ATOMIC_ACQUIRE, "agent");
;             asm volatile("s_waitcnt vmcnt(0)" ::: "memory");
;         }
;     }
;     __syncthreads();
.LBB0_439:
	s_or_b64 exec, exec, s[0:1]
	s_cmp_lg_u32 s42, 0x100
	s_cbranch_scc1 .Lkv2_skip
	s_bitcmp1_b32 s71, 3
	s_cbranch_scc0 .Lkv2_skip
	v_readfirstlane_b32 s3, v208
	s_lshr_b32 s3, s3, 6
	s_cmp_lg_u32 s3, 1
	s_cbranch_scc1 .Lkv2_skip
	s_cmp_lt_u32 s71, 0x74
	s_cbranch_scc1 .Lkv2_now
	v_mov_b32_e32 v228, 0x20020
	ds_read_b32 v228, v228
	s_and_b32 s3, s2, 15
	s_lshl_b32 s3, s3, 8
	s_add_u32 s6, s78, 0x1701400
	s_addc_u32 s7, s79, 0
	s_add_u32 s6, s6, s3
	s_addc_u32 s7, s7, 0
	s_lshl_b32 s8, s66, 2
	s_add_i32 s8, s8, 3
	s_waitcnt lgkmcnt(0)
	v_readfirstlane_b32 s9, v228
	s_nop 3
	s_cmp_eq_u32 s9, 0
	s_cbranch_scc1 .Lkv2_now
	s_mul_i32 s8, s8, s9
	s_sub_i32 s8, s8, 3
	s_mov_b32 s9, 0
.Lkv2_poll:
	global_load_dword v228, v173, s[6:7] sc1
	s_waitcnt vmcnt(0)
	v_readfirstlane_b32 s3, v228
	s_nop 3
	s_cmp_ge_u32 s3, s8
	s_cbranch_scc1 .Lkv2_now
	s_sleep 4
	s_add_i32 s9, s9, 1
	s_cmp_lt_u32 s9, 0x1000
	s_cbranch_scc1 .Lkv2_poll
.Lkv2_now:
	s_lshr_b32 s3, s71, 4
	s_lshl_b32 s3, s3, 3
	s_and_b32 s4, s71, 7
	s_or_b32 s3, s3, s4
	s_lshl_b32 s4, s66, 7
	s_add_i32 s3, s3, s4
	s_lshl_b32 s3, s3, 16
	v_readlane_b32 s6, v253, 14
	v_readlane_b32 s7, v253, 15
	v_readlane_b32 s8, v253, 16
	v_readlane_b32 s9, v253, 17
	s_add_u32 s6, s6, s3
	s_addc_u32 s7, s7, 0
	s_add_u32 s8, s8, s3
	s_addc_u32 s9, s9, 0
	v_and_b32_e32 v228, 63, v208
	v_lshlrev_b32_e32 v228, 7, v228
	global_load_dword v227, v228, s[6:7]
	global_load_dword v227, v228, s[8:9]
	v_add_u32_e32 v228, 0x2000, v228
	global_load_dword v227, v228, s[6:7]
	global_load_dword v227, v228, s[8:9]
	v_add_u32_e32 v228, 0x2000, v228
	global_load_dword v227, v228, s[6:7]
	global_load_dword v227, v228, s[8:9]
	v_add_u32_e32 v228, 0x2000, v228
	global_load_dword v227, v228, s[6:7]
	global_load_dword v227, v228, s[8:9]
	v_add_u32_e32 v228, 0x2000, v228
	global_load_dword v227, v228, s[6:7]
	global_load_dword v227, v228, s[8:9]
	v_add_u32_e32 v228, 0x2000, v228
	global_load_dword v227, v228, s[6:7]
	global_load_dword v227, v228, s[8:9]
	v_add_u32_e32 v228, 0x2000, v228
	global_load_dword v227, v228, s[6:7]
	global_load_dword v227, v228, s[8:9]
	v_add_u32_e32 v228, 0x2000, v228
	global_load_dword v227, v228, s[6:7]
	global_load_dword v227, v228, s[8:9]
